# P2 K-loop: waves 4-7 run a second loop copy that issues LDS-DMA during MFMA group 1 instead of group 3 (de-correlate DMA issue stalls of SIMD wave pairs)
# baseline (speedup 1.0000x reference)
; DI int tid_() { int t = threadIdx.x; asm volatile("" : "+v"(t)); return t; }
; DI void wait_vm0() { asm volatile("s_waitcnt vmcnt(0)" ::: "memory"); }
; DI void bar_() { __builtin_amdgcn_s_barrier(); }
; #define SB_ __builtin_amdgcn_sched_barrier(0)
; template <int TM, int TN, int WM, int WN, bool SUMSQ, int NST, class AF, class BF, class AFN, class BFN>
; DI void gemm8x(f32x16 (&acc)[TM][TN], AF arow, BF brow, int K, char* smem, float& sumsq, bool pre, bool hasNext, AFN arowN, BFN browN) {
;     ...
;   const int t = tid_(), lane = t & 63, w = t >> 6, r = lane & 31, hh = lane >> 5;
;   const int wm = w % WM, wn = w / WM;
;   const int row0 = t >> 3;
;   const int c = (t & 7) ^ ((row0 >> 1) & 7);
;   const bool a0v = row0 < RA, a1v = row0 + 64 < RA, a2v = row0 + 128 < RA, a3v = row0 + 192 < RA;
;   const bool b0v = row0 < RB, b1v = row0 + 64 < RB, b2v = row0 + 128 < RB, b3v = row0 + 192 < RB;
;   const bf16_t* pa0 = arow(a0v ? row0 : 0) + c * 8;
;   const bf16_t* pa1 = arow(a1v ? row0 + 64 : 0) + c * 8;
;   const bf16_t* pa2 = arow(a2v ? row0 + 128 : 0) + c * 8;
;   const bf16_t* pa3 = arow(a3v ? row0 + 192 : 0) + c * 8;
;   const bf16_t* pb0 = brow(b0v ? row0 : 0) + c * 8;
;   const bf16_t* pb1 = brow(b1v ? row0 + 64 : 0) + c * 8;
;   const bf16_t* pb2 = brow(b2v ? row0 + 128 : 0) + c * 8;
;   const bf16_t* pb3 = brow(b3v ? row0 + 192 : 0) + c * 8;
;   if (!pre) {
;     char* l_ = smem + t * 16; char* m_ = l_ + RA * LDR;
;     if (a0v) GLDS(pa0, l_); if (a1v) GLDS(pa1, l_ + 8192); if (a2v) GLDS(pa2, l_ + 16384); if (a3v) GLDS(pa3, l_ + 24576);
;     if (b0v) GLDS(pb0, m_); if (b1v) GLDS(pb1, m_ + 8192); if (b2v) GLDS(pb2, m_ + 16384); if (b3v) GLDS(pb3, m_ + 24576);
;   }
;   if (NST == 3) {
;     char* l_ = smem + STAGE + t * 16; char* m_ = l_ + RA * LDR;
;     GLDS(pa0 + 64, l_); GLDS(pa1 + 64, l_ + 8192); GLDS(pa2 + 64, l_ + 16384); GLDS(pa3 + 64, l_ + 24576);
;     GLDS(pb0 + 64, m_); GLDS(pb1 + 64, m_ + 8192);
;     asm volatile("s_waitcnt vmcnt(6)" ::: "memory");
;   } else wait_vm0();
;   bar_();
;   const int nk = K >> 6;
;   const int sw = (r >> 1) & 7;
;   const int aoff = (wm * TM * 32 + r) * LDR, boff = RA * LDR + (wn * TN * 32 + r) * LDR;
;     ...
;     LOADF(a0, b0, 0);
;     LOADF(a1, b1, 1);
;     SB_;
;     if (issue) { if (a0v) GLDS(q0, l_); if (a1v) GLDS(q1, l_ + 8192); }
.LBB0_222:
	v_ashrrev_i32_e32 v2, 6, v1
	v_lshrrev_b32_e32 v4, 31, v1
	v_add_u32_e32 v4, v2, v4
	v_and_b32_e32 v5, 0x3fffe, v4
	v_bfe_u32 v3, v1, 5, 1
	v_sub_u32_e32 v2, v2, v5
	v_lshrrev_b32_e32 v5, 1, v1
	v_bfe_u32 v6, v1, 1, 3
	v_lshlrev_b32_e32 v1, 7, v1
	v_and_b32_e32 v218, 0xf80, v1
	v_lshlrev_b32_e32 v1, 12, v4
	v_and_b32_e32 v219, 0xffffe000, v1
	v_bitop3_b32 v1, v5, v3, 7 bitop3:0x6c
	v_lshlrev_b32_e32 v216, 4, v1
	v_bitop3_b32 v1, v3, v6, 2 bitop3:0x36
	v_lshlrev_b32_e32 v215, 4, v1
	v_bitop3_b32 v1, v3, v6, 4 bitop3:0x36
	v_lshlrev_b32_e32 v214, 4, v1
	v_bitop3_b32 v1, v3, v6, 6 bitop3:0x36
	v_and_b32_e32 v0, 7, v0
	v_lshl_or_b32 v217, v2, 14, v218
	v_lshlrev_b32_e32 v213, 4, v1
	v_lshl_add_u64 v[2:3], s[46:47], 0, v[188:189]
	v_lshlrev_b32_e32 v0, 4, v0
	v_mov_b32_e32 v1, v185
	v_lshl_add_u64 v[2:3], v[2:3], 0, v[0:1]
	v_lshl_add_u64 v[196:197], s[26:27], 0, v[2:3]
	v_lshl_add_u64 v[2:3], s[46:47], 0, v[190:191]
	v_lshl_add_u64 v[2:3], v[2:3], 0, v[0:1]
	v_lshl_add_u64 v[198:199], s[26:27], 0, v[2:3]
	v_lshl_add_u64 v[2:3], s[46:47], 0, v[192:193]
	v_lshl_add_u64 v[2:3], v[2:3], 0, v[0:1]
	v_lshl_add_u64 v[200:201], s[26:27], 0, v[2:3]
	v_lshl_add_u64 v[2:3], s[46:47], 0, v[194:195]
	v_lshl_add_u64 v[2:3], v[2:3], 0, v[0:1]
	v_lshl_add_u64 v[202:203], s[26:27], 0, v[2:3]
	v_lshl_add_u64 v[2:3], s[44:45], 0, v[188:189]
	v_lshl_add_u64 v[2:3], v[2:3], 0, v[0:1]
	v_lshl_add_u64 v[204:205], s[28:29], 0, v[2:3]
	v_lshl_add_u64 v[2:3], s[44:45], 0, v[190:191]
	v_lshl_add_u64 v[2:3], v[2:3], 0, v[0:1]
	v_lshl_add_u64 v[206:207], s[28:29], 0, v[2:3]
	v_lshl_add_u64 v[2:3], s[44:45], 0, v[192:193]
	v_lshl_add_u64 v[2:3], v[2:3], 0, v[0:1]
	v_lshl_add_u64 v[208:209], s[28:29], 0, v[2:3]
	v_lshl_add_u64 v[2:3], s[44:45], 0, v[194:195]
	s_waitcnt vmcnt(0)
	v_lshl_add_u64 v[0:1], v[2:3], 0, v[0:1]
	v_lshl_add_u64 v[210:211], s[28:29], 0, v[0:1]
	v_mov_b32_e32 v0, 0
	v_or_b32_e32 v222, v218, v219
	s_mov_b32 s13, 0
	s_mov_b64 s[44:45], 0
	v_mov_b32_e32 v1, v0
	v_mov_b32_e32 v2, v0
	v_mov_b32_e32 v3, v0
	v_mov_b32_e32 v4, v0
	v_mov_b32_e32 v5, v0
	v_mov_b32_e32 v6, v0
	v_mov_b32_e32 v7, v0
	v_mov_b32_e32 v8, v0
	v_mov_b32_e32 v9, v0
	v_mov_b32_e32 v10, v0
	v_mov_b32_e32 v11, v0
	v_mov_b32_e32 v12, v0
	v_mov_b32_e32 v13, v0
	v_mov_b32_e32 v14, v0
	v_mov_b32_e32 v15, v0
	v_mov_b32_e32 v64, v0
	v_mov_b32_e32 v65, v0
	v_mov_b32_e32 v66, v0
	v_mov_b32_e32 v67, v0
	v_mov_b32_e32 v68, v0
	v_mov_b32_e32 v69, v0
	v_mov_b32_e32 v70, v0
	v_mov_b32_e32 v71, v0
	v_mov_b32_e32 v72, v0
	v_mov_b32_e32 v73, v0
	v_mov_b32_e32 v74, v0
	v_mov_b32_e32 v75, v0
	v_mov_b32_e32 v76, v0
	v_mov_b32_e32 v77, v0
	v_mov_b32_e32 v78, v0
	v_mov_b32_e32 v79, v0
	v_mov_b32_e32 v16, v0
	v_mov_b32_e32 v17, v0
	v_mov_b32_e32 v18, v0
	v_mov_b32_e32 v19, v0
	v_mov_b32_e32 v20, v0
	v_mov_b32_e32 v21, v0
	v_mov_b32_e32 v22, v0
	v_mov_b32_e32 v23, v0
	v_mov_b32_e32 v24, v0
	v_mov_b32_e32 v25, v0
	v_mov_b32_e32 v26, v0
	v_mov_b32_e32 v27, v0
	v_mov_b32_e32 v28, v0
	v_mov_b32_e32 v29, v0
	v_mov_b32_e32 v30, v0
	v_mov_b32_e32 v31, v0
	v_mov_b32_e32 v80, v0
	v_mov_b32_e32 v81, v0
	v_mov_b32_e32 v82, v0
	v_mov_b32_e32 v83, v0
	v_mov_b32_e32 v84, v0
	v_mov_b32_e32 v85, v0
	v_mov_b32_e32 v86, v0
	v_mov_b32_e32 v87, v0
	v_mov_b32_e32 v88, v0
	v_mov_b32_e32 v89, v0
	v_mov_b32_e32 v90, v0
	v_mov_b32_e32 v91, v0
	v_mov_b32_e32 v92, v0
	v_mov_b32_e32 v93, v0
	v_mov_b32_e32 v94, v0
	v_mov_b32_e32 v95, v0
	v_mov_b32_e32 v32, v0
	v_mov_b32_e32 v33, v0
	v_mov_b32_e32 v34, v0
	v_mov_b32_e32 v35, v0
	v_mov_b32_e32 v36, v0
	v_mov_b32_e32 v37, v0
	v_mov_b32_e32 v38, v0
	v_mov_b32_e32 v39, v0
	v_mov_b32_e32 v40, v0
	v_mov_b32_e32 v41, v0
	v_mov_b32_e32 v42, v0
	v_mov_b32_e32 v43, v0
	v_mov_b32_e32 v44, v0
	v_mov_b32_e32 v45, v0
	v_mov_b32_e32 v46, v0
	v_mov_b32_e32 v47, v0
	v_mov_b32_e32 v96, v0
	v_mov_b32_e32 v97, v0
	v_mov_b32_e32 v98, v0
	v_mov_b32_e32 v99, v0
	v_mov_b32_e32 v100, v0
	v_mov_b32_e32 v101, v0
	v_mov_b32_e32 v102, v0
	v_mov_b32_e32 v103, v0
	v_mov_b32_e32 v104, v0
	v_mov_b32_e32 v105, v0
	v_mov_b32_e32 v106, v0
	v_mov_b32_e32 v107, v0
	v_mov_b32_e32 v108, v0
	v_mov_b32_e32 v109, v0
	v_mov_b32_e32 v110, v0
	v_mov_b32_e32 v111, v0
	v_mov_b32_e32 v48, v0
	v_mov_b32_e32 v49, v0
	v_mov_b32_e32 v50, v0
	v_mov_b32_e32 v51, v0
	v_mov_b32_e32 v52, v0
	v_mov_b32_e32 v53, v0
	v_mov_b32_e32 v54, v0
	v_mov_b32_e32 v55, v0
	v_mov_b32_e32 v56, v0
	v_mov_b32_e32 v57, v0
	v_mov_b32_e32 v58, v0
	v_mov_b32_e32 v59, v0
	v_mov_b32_e32 v60, v0
	v_mov_b32_e32 v61, v0
	v_mov_b32_e32 v62, v0
	v_mov_b32_e32 v63, v0
	v_mov_b32_e32 v112, v0
	v_mov_b32_e32 v113, v0
	v_mov_b32_e32 v114, v0
	v_mov_b32_e32 v115, v0
	v_mov_b32_e32 v116, v0
	v_mov_b32_e32 v117, v0
	v_mov_b32_e32 v118, v0
	v_mov_b32_e32 v119, v0
	v_mov_b32_e32 v120, v0
	v_mov_b32_e32 v121, v0
	v_mov_b32_e32 v122, v0
	v_mov_b32_e32 v123, v0
	v_mov_b32_e32 v124, v0
	v_mov_b32_e32 v125, v0
	v_mov_b32_e32 v126, v0
	v_mov_b32_e32 v127, v0
	s_barrier
	v_readfirstlane_b32 s66, v212
	s_and_b32 s37, s13, 0x10000
	v_add_u32_e32 v225, s37, v222
	v_add_u32_e32 v224, s37, v217
	s_xor_b32 s37, s37, 0x10000
	s_add_i32 s37, s37, s66
	v_add_u32_e32 v226, v225, v216
	v_add_u32_e32 v227, v224, v216
	ds_read_b128 v[164:167], v226 offset:32768
	ds_read_b128 v[172:175], v227
	ds_read_b128 v[156:159], v226 offset:36864
	ds_read_b128 v[168:171], v227 offset:4096
	ds_read_b128 v[160:163], v227 offset:8192
	ds_read_b128 v[152:155], v227 offset:12288
	s_cmp_ge_u32 s66, 0x1000
	s_cbranch_scc1 .Lp2b_g0
	s_mov_b32 m0, s37
	v_lshl_add_u64 v[228:229], v[196:197], 0, s[44:45]
	global_load_lds_dwordx4 v[228:229], off
	s_add_u32 m0, s37, 0x2000
	v_lshl_add_u64 v[230:231], v[198:199], 0, s[44:45]
	global_load_lds_dwordx4 v[230:231], off
	s_add_u32 m0, s37, 0x4000
	v_lshl_add_u64 v[228:229], v[200:201], 0, s[44:45]
	global_load_lds_dwordx4 v[228:229], off
	s_add_u32 m0, s37, 0x6000
	v_lshl_add_u64 v[230:231], v[202:203], 0, s[44:45]
	global_load_lds_dwordx4 v[230:231], off
	s_add_u32 m0, s37, 0x8000
	v_lshl_add_u64 v[228:229], v[204:205], 0, s[44:45]
	global_load_lds_dwordx4 v[228:229], off
	s_add_u32 m0, s37, 0xa000
	v_lshl_add_u64 v[230:231], v[206:207], 0, s[44:45]
	global_load_lds_dwordx4 v[230:231], off
	s_add_u32 m0, s37, 0xc000
	v_lshl_add_u64 v[228:229], v[208:209], 0, s[44:45]
	global_load_lds_dwordx4 v[228:229], off
	s_add_u32 m0, s37, 0xe000
	v_lshl_add_u64 v[230:231], v[210:211], 0, s[44:45]
	global_load_lds_dwordx4 v[230:231], off
	s_branch .Lp2_g0

; DI void wait_vm0() { asm volatile("s_waitcnt vmcnt(0)" ::: "memory"); }
; DI void bar_() { __builtin_amdgcn_s_barrier(); }
; #define GLDS(gp, lp) __builtin_amdgcn_global_load_lds((const unsigned*)(gp), (__attribute__((address_space(3))) unsigned*)(lp), 16, 0, 0)
; #define SB_ __builtin_amdgcn_sched_barrier(0)
; template <int TM, int TN, int WM, int WN, bool SUMSQ, int NST, class AF, class BF, class AFN, class BFN>
; DI void gemm8x(f32x16 (&acc)[TM][TN], AF arow, BF brow, int K, char* smem, float& sumsq, bool pre, bool hasNext, AFN arowN, BFN browN) {
;     ...
;   auto compute = [&](const char* cur, char* nxt, bool issue, const bf16_t* q0, const bf16_t* q1, const bf16_t* q2, const bf16_t* q3,
;                      const bf16_t* s0, const bf16_t* s1, const bf16_t* s2, const bf16_t* s3) {
;     const char* As = cur + aoff;
;     const char* Bs = cur + boff;
;     char* l_ = nxt + t * 16; char* m_ = l_ + RA * LDR;
;     bf16x8 a0[TM], b0[TN], a1[TM], b1[TN];
;     ...
;     LOADF(a0, b0, 0);
;     LOADF(a1, b1, 1);
;     SB_;
;     if (issue) { if (a0v) GLDS(q0, l_); if (a1v) GLDS(q1, l_ + 8192); }
;     SB_;
;     __builtin_amdgcn_s_setprio(1);
;     MMF(a0, b0);
;     LOADF(a0, b0, 2);
;     SB_;
;     if (issue) { if (a2v) GLDS(q2, l_ + 16384); if (a3v) GLDS(q3, l_ + 24576); }
;     SB_;
;     MMF(a1, b1);
;     LOADF(a1, b1, 3);
;     SB_;
;     if (issue) { if (b0v) GLDS(s0, m_); if (b1v) GLDS(s1, m_ + 8192); }
;     SB_;
;     MMF(a0, b0);
;     SB_;
;     if (issue) { if (b2v) GLDS(s2, m_ + 16384); if (b3v) GLDS(s3, m_ + 24576); }
;     SB_;
;     MMF(a1, b1);
;     __builtin_amdgcn_s_setprio(0);
;   };
;   int sc_ = 0;
;   for (int kt = 0; kt < nk - 1; ++kt) {
;     SB_;
;     if (NST == 2) {
;       const int ko = (kt + 1) * 64;
;       compute(smem + (kt & 1) * STAGE, smem + ((kt + 1) & 1) * STAGE, true, pa0 + ko, pa1 + ko, pa2 + ko, pa3 + ko, pb0 + ko, pb1 + ko, pb2 + ko, pb3 + ko);
;       SB_;
;       wait_vm0(); bar_();
;     } else {
;       const int ko = (kt + 2) * 64; const bool iss = kt + 2 < nk;
;       const int sn = (sc_ == 0) ? 2 : sc_ - 1;
;       compute(smem + sc_ * STAGE, smem + sn * STAGE, iss, pa0 + ko, pa1 + ko, pa2 + ko, pa3 + ko, pb0 + ko, pb1 + ko, pb2 + ko, pb3 + ko);
;       SB_;
;       if (iss) asm volatile("s_waitcnt vmcnt(6)" ::: "memory"); else wait_vm0();
;       bar_();
;       sc_ = (sc_ == 2) ? 0 : sc_ + 1;
;     }
;   }
.Lp2_g0:
	s_setprio 1
	v_add_u32_e32 v226, v225, v215
	v_add_u32_e32 v227, v224, v215
	s_waitcnt lgkmcnt(0)
	v_mfma_f32_32x32x16_bf16 v[112:127], v[172:175], v[164:167], v[112:127]
	ds_read_b128 v[140:143], v226 offset:32768
	ds_read_b128 v[148:151], v227
	v_mfma_f32_32x32x16_bf16 v[48:63], v[172:175], v[156:159], v[48:63]
	ds_read_b128 v[132:135], v226 offset:36864
	ds_read_b128 v[144:147], v227 offset:4096
	v_mfma_f32_32x32x16_bf16 v[96:111], v[168:171], v[164:167], v[96:111]
	ds_read_b128 v[136:139], v227 offset:8192
	v_mfma_f32_32x32x16_bf16 v[32:47], v[168:171], v[156:159], v[32:47]
	ds_read_b128 v[128:131], v227 offset:12288
	v_mfma_f32_32x32x16_bf16 v[80:95], v[160:163], v[164:167], v[80:95]
	v_mfma_f32_32x32x16_bf16 v[16:31], v[160:163], v[156:159], v[16:31]
	v_mfma_f32_32x32x16_bf16 v[64:79], v[152:155], v[164:167], v[64:79]
	v_mfma_f32_32x32x16_bf16 v[0:15], v[152:155], v[156:159], v[0:15]
	v_add_u32_e32 v226, v225, v214
	v_add_u32_e32 v227, v224, v214
	s_waitcnt lgkmcnt(0)
	v_mfma_f32_32x32x16_bf16 v[112:127], v[148:151], v[140:143], v[112:127]
	ds_read_b128 v[164:167], v226 offset:32768
	ds_read_b128 v[172:175], v227
	v_mfma_f32_32x32x16_bf16 v[48:63], v[148:151], v[132:135], v[48:63]
	ds_read_b128 v[156:159], v226 offset:36864
	ds_read_b128 v[168:171], v227 offset:4096
	v_mfma_f32_32x32x16_bf16 v[96:111], v[144:147], v[140:143], v[96:111]
	ds_read_b128 v[160:163], v227 offset:8192
	v_mfma_f32_32x32x16_bf16 v[32:47], v[144:147], v[132:135], v[32:47]
	ds_read_b128 v[152:155], v227 offset:12288
	v_mfma_f32_32x32x16_bf16 v[80:95], v[136:139], v[140:143], v[80:95]
	v_mfma_f32_32x32x16_bf16 v[16:31], v[136:139], v[132:135], v[16:31]
	v_mfma_f32_32x32x16_bf16 v[64:79], v[128:131], v[140:143], v[64:79]
	v_mfma_f32_32x32x16_bf16 v[0:15], v[128:131], v[132:135], v[0:15]
	v_add_u32_e32 v226, v225, v213
	v_add_u32_e32 v227, v224, v213
	s_waitcnt lgkmcnt(0)
	v_mfma_f32_32x32x16_bf16 v[112:127], v[172:175], v[164:167], v[112:127]
	ds_read_b128 v[140:143], v226 offset:32768
	ds_read_b128 v[148:151], v227
	v_mfma_f32_32x32x16_bf16 v[48:63], v[172:175], v[156:159], v[48:63]
	ds_read_b128 v[132:135], v226 offset:36864
	ds_read_b128 v[144:147], v227 offset:4096
	v_mfma_f32_32x32x16_bf16 v[96:111], v[168:171], v[164:167], v[96:111]
	ds_read_b128 v[136:139], v227 offset:8192
	v_mfma_f32_32x32x16_bf16 v[32:47], v[168:171], v[156:159], v[32:47]
	ds_read_b128 v[128:131], v227 offset:12288
	v_mfma_f32_32x32x16_bf16 v[80:95], v[160:163], v[164:167], v[80:95]
	v_mfma_f32_32x32x16_bf16 v[16:31], v[160:163], v[156:159], v[16:31]
	v_mfma_f32_32x32x16_bf16 v[64:79], v[152:155], v[164:167], v[64:79]
	v_mfma_f32_32x32x16_bf16 v[0:15], v[152:155], v[156:159], v[0:15]
	s_setprio 0
	s_waitcnt vmcnt(0) lgkmcnt(0)
	s_add_i32 s13, s13, 0x10000
	s_add_u32 s44, s44, 0x80
	s_addc_u32 s45, s45, 0
	s_cmpk_eq_i32 s44, 0x780
	s_barrier
	s_cbranch_scc0 .Lp2_loop
	s_branch .Lp2_peel
.Lp2b_loop:
	s_and_b32 s37, s13, 0x10000
	v_add_u32_e32 v225, s37, v222
	v_add_u32_e32 v224, s37, v217
	s_xor_b32 s37, s37, 0x10000
	s_add_i32 s37, s37, s66
	v_add_u32_e32 v226, v225, v216
	v_add_u32_e32 v227, v224, v216
	s_setprio 1
	v_mfma_f32_32x32x16_bf16 v[112:127], v[148:151], v[140:143], v[112:127]
	ds_read_b128 v[164:167], v226 offset:32768
	ds_read_b128 v[172:175], v227
	v_mfma_f32_32x32x16_bf16 v[48:63], v[148:151], v[132:135], v[48:63]
	ds_read_b128 v[156:159], v226 offset:36864
	ds_read_b128 v[168:171], v227 offset:4096
	v_mfma_f32_32x32x16_bf16 v[96:111], v[144:147], v[140:143], v[96:111]
	ds_read_b128 v[160:163], v227 offset:8192
	v_mfma_f32_32x32x16_bf16 v[32:47], v[144:147], v[132:135], v[32:47]
	ds_read_b128 v[152:155], v227 offset:12288
	v_mfma_f32_32x32x16_bf16 v[80:95], v[136:139], v[140:143], v[80:95]
	v_mfma_f32_32x32x16_bf16 v[16:31], v[136:139], v[132:135], v[16:31]
	v_mfma_f32_32x32x16_bf16 v[64:79], v[128:131], v[140:143], v[64:79]
	v_mfma_f32_32x32x16_bf16 v[0:15], v[128:131], v[132:135], v[0:15]
.Lp2b_g0:
	s_setprio 1
	v_add_u32_e32 v226, v225, v215
	v_add_u32_e32 v227, v224, v215
	s_waitcnt lgkmcnt(0)
	v_mfma_f32_32x32x16_bf16 v[112:127], v[172:175], v[164:167], v[112:127]
	ds_read_b128 v[140:143], v226 offset:32768
	ds_read_b128 v[148:151], v227
	v_mfma_f32_32x32x16_bf16 v[48:63], v[172:175], v[156:159], v[48:63]
	ds_read_b128 v[132:135], v226 offset:36864
	ds_read_b128 v[144:147], v227 offset:4096
	v_mfma_f32_32x32x16_bf16 v[96:111], v[168:171], v[164:167], v[96:111]
	ds_read_b128 v[136:139], v227 offset:8192
	v_mfma_f32_32x32x16_bf16 v[32:47], v[168:171], v[156:159], v[32:47]
	ds_read_b128 v[128:131], v227 offset:12288
	v_mfma_f32_32x32x16_bf16 v[80:95], v[160:163], v[164:167], v[80:95]
	v_mfma_f32_32x32x16_bf16 v[16:31], v[160:163], v[156:159], v[16:31]
	v_mfma_f32_32x32x16_bf16 v[64:79], v[152:155], v[164:167], v[64:79]
	v_mfma_f32_32x32x16_bf16 v[0:15], v[152:155], v[156:159], v[0:15]
	v_add_u32_e32 v226, v225, v214
	v_add_u32_e32 v227, v224, v214
	s_waitcnt lgkmcnt(0)
; DI void wait_vm0() { asm volatile("s_waitcnt vmcnt(0)" ::: "memory"); }
; DI void bar_() { __builtin_amdgcn_s_barrier(); }
; #define GLDS(gp, lp) __builtin_amdgcn_global_load_lds((const unsigned*)(gp), (__attribute__((address_space(3))) unsigned*)(lp), 16, 0, 0)
; #define SB_ __builtin_amdgcn_sched_barrier(0)
; template <int TM, int TN, int WM, int WN, bool SUMSQ, int NST, class AF, class BF, class AFN, class BFN>
; DI void gemm8x(f32x16 (&acc)[TM][TN], AF arow, BF brow, int K, char* smem, float& sumsq, bool pre, bool hasNext, AFN arowN, BFN browN) {
;     ...
;   auto compute = [&](const char* cur, char* nxt, bool issue, const bf16_t* q0, const bf16_t* q1, const bf16_t* q2, const bf16_t* q3,
;                      const bf16_t* s0, const bf16_t* s1, const bf16_t* s2, const bf16_t* s3) {
;     const char* As = cur + aoff;
;     const char* Bs = cur + boff;
;     char* l_ = nxt + t * 16; char* m_ = l_ + RA * LDR;
;     bf16x8 a0[TM], b0[TN], a1[TM], b1[TN];
;     ...
;     LOADF(a0, b0, 0);
;     LOADF(a1, b1, 1);
;     SB_;
;     if (issue) { if (a0v) GLDS(q0, l_); if (a1v) GLDS(q1, l_ + 8192); }
;     SB_;
;     __builtin_amdgcn_s_setprio(1);
;     MMF(a0, b0);
;     LOADF(a0, b0, 2);
;     SB_;
;     if (issue) { if (a2v) GLDS(q2, l_ + 16384); if (a3v) GLDS(q3, l_ + 24576); }
;     SB_;
;     MMF(a1, b1);
;     LOADF(a1, b1, 3);
;     SB_;
;     if (issue) { if (b0v) GLDS(s0, m_); if (b1v) GLDS(s1, m_ + 8192); }
;     SB_;
;     MMF(a0, b0);
;     SB_;
;     if (issue) { if (b2v) GLDS(s2, m_ + 16384); if (b3v) GLDS(s3, m_ + 24576); }
;     SB_;
;     MMF(a1, b1);
;     __builtin_amdgcn_s_setprio(0);
;   };
;   int sc_ = 0;
;   for (int kt = 0; kt < nk - 1; ++kt) {
;     SB_;
;     if (NST == 2) {
;       const int ko = (kt + 1) * 64;
;       compute(smem + (kt & 1) * STAGE, smem + ((kt + 1) & 1) * STAGE, true, pa0 + ko, pa1 + ko, pa2 + ko, pa3 + ko, pb0 + ko, pb1 + ko, pb2 + ko, pb3 + ko);
;       SB_;
;       wait_vm0(); bar_();
;     } else {
;       const int ko = (kt + 2) * 64; const bool iss = kt + 2 < nk;
;       const int sn = (sc_ == 0) ? 2 : sc_ - 1;
;       compute(smem + sc_ * STAGE, smem + sn * STAGE, iss, pa0 + ko, pa1 + ko, pa2 + ko, pa3 + ko, pb0 + ko, pb1 + ko, pb2 + ko, pb3 + ko);
;       SB_;
;       if (iss) asm volatile("s_waitcnt vmcnt(6)" ::: "memory"); else wait_vm0();
;       bar_();
;       sc_ = (sc_ == 2) ? 0 : sc_ + 1;
;     }
;   }
	v_mfma_f32_32x32x16_bf16 v[112:127], v[148:151], v[140:143], v[112:127]
	ds_read_b128 v[164:167], v226 offset:32768
	ds_read_b128 v[172:175], v227
	s_mov_b32 m0, s37
	v_lshl_add_u64 v[228:229], v[196:197], 0, s[44:45]
	global_load_lds_dwordx4 v[228:229], off
	v_mfma_f32_32x32x16_bf16 v[48:63], v[148:151], v[132:135], v[48:63]
	ds_read_b128 v[156:159], v226 offset:36864
	ds_read_b128 v[168:171], v227 offset:4096
	s_add_u32 m0, s37, 0x2000
	v_lshl_add_u64 v[230:231], v[198:199], 0, s[44:45]
	global_load_lds_dwordx4 v[230:231], off
	v_mfma_f32_32x32x16_bf16 v[96:111], v[144:147], v[140:143], v[96:111]
	ds_read_b128 v[160:163], v227 offset:8192
	s_add_u32 m0, s37, 0x4000
	v_lshl_add_u64 v[228:229], v[200:201], 0, s[44:45]
	global_load_lds_dwordx4 v[228:229], off
	v_mfma_f32_32x32x16_bf16 v[32:47], v[144:147], v[132:135], v[32:47]
	ds_read_b128 v[152:155], v227 offset:12288
	s_add_u32 m0, s37, 0x6000
	v_lshl_add_u64 v[230:231], v[202:203], 0, s[44:45]
	global_load_lds_dwordx4 v[230:231], off
	v_mfma_f32_32x32x16_bf16 v[80:95], v[136:139], v[140:143], v[80:95]
	s_add_u32 m0, s37, 0x8000
	v_lshl_add_u64 v[228:229], v[204:205], 0, s[44:45]
	global_load_lds_dwordx4 v[228:229], off
	v_mfma_f32_32x32x16_bf16 v[16:31], v[136:139], v[132:135], v[16:31]
	s_add_u32 m0, s37, 0xa000
	v_lshl_add_u64 v[230:231], v[206:207], 0, s[44:45]
	global_load_lds_dwordx4 v[230:231], off
	v_mfma_f32_32x32x16_bf16 v[64:79], v[128:131], v[140:143], v[64:79]
	s_add_u32 m0, s37, 0xc000
	v_lshl_add_u64 v[228:229], v[208:209], 0, s[44:45]
	global_load_lds_dwordx4 v[228:229], off
	v_mfma_f32_32x32x16_bf16 v[0:15], v[128:131], v[132:135], v[0:15]
	s_add_u32 m0, s37, 0xe000
	v_lshl_add_u64 v[230:231], v[210:211], 0, s[44:45]
	global_load_lds_dwordx4 v[230:231], off
	v_add_u32_e32 v226, v225, v213
	v_add_u32_e32 v227, v224, v213
	s_waitcnt lgkmcnt(0)
	v_mfma_f32_32x32x16_bf16 v[112:127], v[172:175], v[164:167], v[112:127]
	ds_read_b128 v[140:143], v226 offset:32768
	ds_read_b128 v[148:151], v227
	v_mfma_f32_32x32x16_bf16 v[48:63], v[172:175], v[156:159], v[48:63]
	ds_read_b128 v[132:135], v226 offset:36864
	ds_read_b128 v[144:147], v227 offset:4096
	v_mfma_f32_32x32x16_bf16 v[96:111], v[168:171], v[164:167], v[96:111]
	ds_read_b128 v[136:139], v227 offset:8192
	v_mfma_f32_32x32x16_bf16 v[32:47], v[168:171], v[156:159], v[32:47]
	ds_read_b128 v[128:131], v227 offset:12288
	v_mfma_f32_32x32x16_bf16 v[80:95], v[160:163], v[164:167], v[80:95]
	v_mfma_f32_32x32x16_bf16 v[16:31], v[160:163], v[156:159], v[16:31]
	v_mfma_f32_32x32x16_bf16 v[64:79], v[152:155], v[164:167], v[64:79]
	v_mfma_f32_32x32x16_bf16 v[0:15], v[152:155], v[156:159], v[0:15]
	s_setprio 0
	s_waitcnt vmcnt(0) lgkmcnt(0)
	s_add_i32 s13, s13, 0x10000
	s_add_u32 s44, s44, 0x80
	s_addc_u32 s45, s45, 0
	s_cmpk_eq_i32 s44, 0x780
	s_barrier
	s_cbranch_scc0 .Lp2b_loop
; DI void lds_sync() { wait_lgkm0(); bar_(); }
; #define GLDS(gp, lp) __builtin_amdgcn_global_load_lds((const unsigned*)(gp), (__attribute__((address_space(3))) unsigned*)(lp), 16, 0, 0)
; #define SB_ __builtin_amdgcn_sched_barrier(0)
; #define LOADF(A_, B_, ks) do { const int po_ = (((ks) * 2 + hh) ^ sw) * 16; \
;       _Pragma("unroll") for (int tm = 0; tm < TM; ++tm) A_[tm] = *(const bf16x8*)(As + tm * 32 * LDR + po_); \
;       _Pragma("unroll") for (int tn = 0; tn < TN; ++tn) B_[tn] = *(const bf16x8*)(Bs + tn * 32 * LDR + po_); } while (0)
; template <int TM, int TN, int WM, int WN, bool SUMSQ, int NST, class AF, class BF, class AFN, class BFN>
; DI void gemm8x(f32x16 (&acc)[TM][TN], AF arow, BF brow, int K, char* smem, float& sumsq, bool pre, bool hasNext, AFN arowN, BFN browN) {
;     ...
;     LOADF(a0, b0, 0);
;     LOADF(a1, b1, 1);
;     SB_;
;     if (issue) { if (a0v) GLDS(q0, l_); if (a1v) GLDS(q1, l_ + 8192); }
;     SB_;
;     __builtin_amdgcn_s_setprio(1);
;     MMF(a0, b0);
;     LOADF(a0, b0, 2);
;     SB_;
;     if (issue) { if (a2v) GLDS(q2, l_ + 16384); if (a3v) GLDS(q3, l_ + 24576); }
;     SB_;
;     MMF(a1, b1);
;     LOADF(a1, b1, 3);
;     SB_;
;     if (issue) { if (b0v) GLDS(s0, m_); if (b1v) GLDS(s1, m_ + 8192); }
;     SB_;
;     MMF(a0, b0);
;     SB_;
;     if (issue) { if (b2v) GLDS(s2, m_ + 16384); if (b3v) GLDS(s3, m_ + 24576); }
;     SB_;
;     MMF(a1, b1);
;     ...
;   } else {
;     const bf16_t *q0 = pa0, *q1 = pa0, *q2 = pa0, *q3 = pa0, *s0 = pa0, *s1 = pa0, *s2 = pa0, *s3 = pa0;
;     if (hasNext) {
;       q0 = arowN(a0v ? row0 : 0) + c * 8; q1 = arowN(a1v ? row0 + 64 : 0) + c * 8; q2 = arowN(a2v ? row0 + 128 : 0) + c * 8; q3 = arowN(a3v ? row0 + 192 : 0) + c * 8;
;       s0 = browN(b0v ? row0 : 0) + c * 8; s1 = browN(b1v ? row0 + 64 : 0) + c * 8; s2 = browN(b2v ? row0 + 128 : 0) + c * 8; s3 = browN(b3v ? row0 + 192 : 0) + c * 8;
;     }
;     SB_;
;     compute(smem + ((nk - 1) & 1) * STAGE, smem, hasNext, q0, q1, q2, q3, s0, s1, s2, s3);
;     SB_;
;     lds_sync();
;   }
.Lp2_peel:
	s_and_b32 s37, s13, 0x10000
	v_add_u32_e32 v225, s37, v222
	v_add_u32_e32 v224, s37, v217
	s_xor_b32 s37, s37, 0x10000
	s_add_i32 s37, s37, s66
	v_add_u32_e32 v226, v225, v216
	v_add_u32_e32 v227, v224, v216
	s_setprio 1
	v_mfma_f32_32x32x16_bf16 v[112:127], v[148:151], v[140:143], v[112:127]
	ds_read_b128 v[164:167], v226 offset:32768
	ds_read_b128 v[172:175], v227
	v_mfma_f32_32x32x16_bf16 v[48:63], v[148:151], v[132:135], v[48:63]
	ds_read_b128 v[156:159], v226 offset:36864
	ds_read_b128 v[168:171], v227 offset:4096
	v_mfma_f32_32x32x16_bf16 v[96:111], v[144:147], v[140:143], v[96:111]
	ds_read_b128 v[160:163], v227 offset:8192
	v_mfma_f32_32x32x16_bf16 v[32:47], v[144:147], v[132:135], v[32:47]
	ds_read_b128 v[152:155], v227 offset:12288
	v_mfma_f32_32x32x16_bf16 v[80:95], v[136:139], v[140:143], v[80:95]
	v_mfma_f32_32x32x16_bf16 v[16:31], v[136:139], v[132:135], v[16:31]
	v_mfma_f32_32x32x16_bf16 v[64:79], v[128:131], v[140:143], v[64:79]
	v_mfma_f32_32x32x16_bf16 v[0:15], v[128:131], v[132:135], v[0:15]
	s_setprio 1
	v_add_u32_e32 v226, v225, v215
	v_add_u32_e32 v227, v224, v215
	s_waitcnt lgkmcnt(0)
	v_mfma_f32_32x32x16_bf16 v[112:127], v[172:175], v[164:167], v[112:127]
	ds_read_b128 v[140:143], v226 offset:32768
	ds_read_b128 v[148:151], v227
	v_mfma_f32_32x32x16_bf16 v[48:63], v[172:175], v[156:159], v[48:63]
	ds_read_b128 v[132:135], v226 offset:36864
	ds_read_b128 v[144:147], v227 offset:4096
	v_mfma_f32_32x32x16_bf16 v[96:111], v[168:171], v[164:167], v[96:111]
	ds_read_b128 v[136:139], v227 offset:8192
	v_mfma_f32_32x32x16_bf16 v[32:47], v[168:171], v[156:159], v[32:47]
	ds_read_b128 v[128:131], v227 offset:12288
	v_mfma_f32_32x32x16_bf16 v[80:95], v[160:163], v[164:167], v[80:95]
	v_mfma_f32_32x32x16_bf16 v[16:31], v[160:163], v[156:159], v[16:31]
	v_mfma_f32_32x32x16_bf16 v[64:79], v[152:155], v[164:167], v[64:79]
	v_mfma_f32_32x32x16_bf16 v[0:15], v[152:155], v[156:159], v[0:15]
	v_add_u32_e32 v226, v225, v214
	v_add_u32_e32 v227, v224, v214
	s_waitcnt lgkmcnt(0)
	v_mfma_f32_32x32x16_bf16 v[112:127], v[148:151], v[140:143], v[112:127]
	ds_read_b128 v[164:167], v226 offset:32768
	ds_read_b128 v[172:175], v227
	v_mfma_f32_32x32x16_bf16 v[48:63], v[148:151], v[132:135], v[48:63]
	ds_read_b128 v[156:159], v226 offset:36864
	ds_read_b128 v[168:171], v227 offset:4096
	v_mfma_f32_32x32x16_bf16 v[96:111], v[144:147], v[140:143], v[96:111]
	ds_read_b128 v[160:163], v227 offset:8192
	v_mfma_f32_32x32x16_bf16 v[32:47], v[144:147], v[132:135], v[32:47]
	ds_read_b128 v[152:155], v227 offset:12288
	v_mfma_f32_32x32x16_bf16 v[80:95], v[136:139], v[140:143], v[80:95]
	v_mfma_f32_32x32x16_bf16 v[16:31], v[136:139], v[132:135], v[16:31]
	v_mfma_f32_32x32x16_bf16 v[64:79], v[128:131], v[140:143], v[64:79]
	v_mfma_f32_32x32x16_bf16 v[0:15], v[128:131], v[132:135], v[0:15]
	v_add_u32_e32 v226, v225, v213
	v_add_u32_e32 v227, v224, v213
	s_waitcnt lgkmcnt(0)
	v_mfma_f32_32x32x16_bf16 v[112:127], v[172:175], v[164:167], v[112:127]
	ds_read_b128 v[140:143], v226 offset:32768
	ds_read_b128 v[148:151], v227
	v_mfma_f32_32x32x16_bf16 v[48:63], v[172:175], v[156:159], v[48:63]
	ds_read_b128 v[132:135], v226 offset:36864
	ds_read_b128 v[144:147], v227 offset:4096
	v_mfma_f32_32x32x16_bf16 v[96:111], v[168:171], v[164:167], v[96:111]
	ds_read_b128 v[136:139], v227 offset:8192
	v_mfma_f32_32x32x16_bf16 v[32:47], v[168:171], v[156:159], v[32:47]
	ds_read_b128 v[128:131], v227 offset:12288
	v_mfma_f32_32x32x16_bf16 v[80:95], v[160:163], v[164:167], v[80:95]
	v_mfma_f32_32x32x16_bf16 v[16:31], v[160:163], v[156:159], v[16:31]
	v_mfma_f32_32x32x16_bf16 v[64:79], v[152:155], v[164:167], v[64:79]
	v_mfma_f32_32x32x16_bf16 v[0:15], v[152:155], v[156:159], v[0:15]
	s_and_b64 vcc, exec, s[40:41]
	s_cbranch_vccz .Lp2_nonext
	s_mov_b32 s43, s31
	s_lshl_b64 s[42:43], s[42:43], 19
	s_add_u32 s42, s14, s42
	s_addc_u32 s43, s15, s43
	s_mov_b32 s13, s31
	v_lshl_add_u64 v[226:227], s[42:43], 0, v[188:189]
	s_lshl_b64 s[12:13], s[12:13], 19
	v_lshl_add_u64 v[186:187], v[226:227], 0, v[184:185]
	v_lshl_add_u64 v[226:227], s[42:43], 0, v[190:191]
	s_add_u32 s12, s16, s12
	v_lshl_add_u64 v[164:165], v[226:227], 0, v[184:185]
	v_lshl_add_u64 v[226:227], s[42:43], 0, v[192:193]
	s_addc_u32 s13, s17, s13
	v_lshl_add_u64 v[206:207], v[226:227], 0, v[184:185]
	v_lshl_add_u64 v[226:227], s[42:43], 0, v[194:195]
	v_lshl_add_u64 v[204:205], v[226:227], 0, v[184:185]
	v_lshl_add_u64 v[226:227], s[12:13], 0, v[188:189]
	v_lshl_add_u64 v[202:203], v[226:227], 0, v[184:185]
	v_lshl_add_u64 v[226:227], s[12:13], 0, v[190:191]
	v_lshl_add_u64 v[200:201], v[226:227], 0, v[184:185]
	v_lshl_add_u64 v[226:227], s[12:13], 0, v[192:193]
	v_lshl_add_u64 v[198:199], v[226:227], 0, v[184:185]
	v_lshl_add_u64 v[226:227], s[12:13], 0, v[194:195]
	v_lshl_add_u64 v[196:197], v[226:227], 0, v[184:185]
	s_mov_b32 m0, s66
	s_nop 0
	global_load_lds_dwordx4 v[186:187], off
	s_add_u32 m0, s66, 0x2000
	s_nop 0
	global_load_lds_dwordx4 v[164:165], off
	s_add_u32 m0, s66, 0x4000
	s_nop 0
	global_load_lds_dwordx4 v[206:207], off
	s_add_u32 m0, s66, 0x6000
	s_nop 0
	global_load_lds_dwordx4 v[204:205], off
	s_add_u32 m0, s66, 0x8000
	s_nop 0
	global_load_lds_dwordx4 v[202:203], off
	s_add_u32 m0, s66, 0xa000
	s_nop 0
	global_load_lds_dwordx4 v[200:201], off
	s_add_u32 m0, s66, 0xc000
	s_nop 0
	global_load_lds_dwordx4 v[198:199], off
	s_add_u32 m0, s66, 0xe000
	s_nop 0
	global_load_lds_dwordx4 v[196:197], off
